# accumulator-adjacent MFMA order in all 40 blocks (dependency-aware), down loop padded
# speedup vs baseline: 1.0157x; 1.0000x over previous
; #define PG8_STAGE(bufoff, gbase, voff) do { _Pragma("unroll") for (int _i = 0; _i < 2; ++_i) \
;         __builtin_amdgcn_global_load_lds((const unsigned*)((const char*)(gbase) + (voff)[_i]), (PG8_LAS unsigned*)(lds + (bufoff) + ldsw + _i * 8192), 16, 0, 0); } while (0)
; #define PG8_LDA(dst, b, h) do { _Pragma("unroll") for (int m = 0; m < 4; ++m) _Pragma("unroll") for (int k = 0; k < 2; ++k) dst[m][k] = *(const PG8_LAS bf16x8*)(lds + PG8_SA(b, h) + aoff + m * 2048 + k * 1024); } while (0)
; #define PG8_LDB(dst, b, h) do { _Pragma("unroll") for (int n = 0; n < 2; ++n) _Pragma("unroll") for (int k = 0; k < 2; ++k) dst[n][k] = *(const PG8_LAS bf16x8*)(lds + PG8_SB(b, h) + boff + n * 2048 + k * 1024); } while (0)
; #define PG8_MMA(ai, bj, At, Bt) do { __builtin_amdgcn_s_setprio(1); _Pragma("unroll") for (int m = 0; m < 4; ++m) _Pragma("unroll") for (int n = 0; n < 2; ++n) _Pragma("unroll") for (int k = 0; k < 2; ++k) \
;         acc[ai][bj][m][n] = __builtin_amdgcn_mfma_f32_16x16x32_bf16(Bt[n][k], At[m][k], acc[ai][bj][m][n], 0, 0, 0); __builtin_amdgcn_s_setprio(0); } while (0)
; #define PG8_WAIT_V(n) asm volatile("s_waitcnt vmcnt(" #n ")" ::: "memory")
; #define PG8_WAIT_L(n) asm volatile("s_waitcnt lgkmcnt(" #n ")" ::: "memory")
; template <class Epi, class Sched, bool ALIGN_EPI = true>
; __device__ __forceinline__ void gemm_phase(PG8_LAS unsigned char* lds, const Gemm g, const Sched& S, const Epi& E, const int tid) {
;     ...
;         for (int t = 0; t < nt; t += 2) {
;             const bool last = (t == nt - 2);
;             const char* a1 = cA + (size_t)(t + 1) * kstep;
;             const char* a2 = last ? nA : cA + (size_t)(t + 2) * kstep; const char* b2 = last ? nB : cB + (size_t)(t + 2) * kstep;
;             const char* a3 = a2 + kstep; const char* b3 = b2 + kstep;
;             if (last && has_next) S.a_ready(nxt);
;             PG8_LDB(B0, 0, 0); PG8_LDB(B1, 0, 1); PG8_SCHED; PG8_LDA(At, 0, 0); PG8_STAGE(PG8_SA(1, 1), a1 + hstepA, voffA);
;             PG8_WAIT_V(8); PG8_WAIT_L(0); PG8_BAR; PG8_MMA(0, 0, At, B0); PG8_MMA(0, 1, At, B1); PG8_BAR; PG8_SCHED;
;             PG8_LDA(At, 0, 1); PG8_STAGE(PG8_SB(0, 0), b2, voffB); PG8_STAGE(PG8_SB(0, 1), b2 + hstepB, voffB); PG8_STAGE(PG8_SA(0, 0), a2, voffA);
;             PG8_WAIT_V(8); PG8_WAIT_L(0); PG8_BAR; PG8_MMA(1, 0, At, B0); PG8_MMA(1, 1, At, B1); PG8_BAR; PG8_SCHED;
.LBB0_426:
	s_add_u32 s15, s12, 0xfff80080
	s_addc_u32 s16, s13, -1
	s_add_i32 s17, 0, 0x10000
	s_cmp_eq_u32 s53, 4
	s_cselect_b32 s63, s1, s16
	s_cselect_b32 s62, s5, s15
	s_cselect_b32 s23, s8, s21
	s_cselect_b32 s22, s9, s20
	s_add_i32 s15, 0, 0x14000
	v_add_u32_e32 v72, s17, v251
	v_add_u32_e32 v136, s15, v251
	ds_read_b128 v[60:63], v72
	ds_read_b128 v[64:67], v72 offset:1024
	ds_read_b128 v[68:71], v72 offset:2048
	ds_read_b128 v[72:75], v72 offset:3072
	ds_read_b128 v[100:103], v136
	ds_read_b128 v[112:115], v136 offset:1024
	ds_read_b128 v[116:119], v136 offset:2048
	ds_read_b128 v[136:139], v136 offset:3072
	v_lshl_add_u64 v[196:197], s[12:13], 0, v[216:217]
	s_add_i32 m0, s11, 0xc000
	ds_read_b128 v[140:143], v252
	ds_read_b128 v[152:155], v252 offset:1024
	ds_read_b128 v[156:159], v252 offset:2048
	ds_read_b128 v[168:171], v252 offset:3072
	ds_read_b128 v[172:175], v252 offset:4096
	ds_read_b128 v[184:187], v252 offset:5120
	ds_read_b128 v[188:191], v252 offset:6144
	ds_read_b128 v[192:195], v252 offset:7168
	global_load_lds_dwordx4 v[196:197], off
	v_lshl_add_u64 v[196:197], s[12:13], 0, v[218:219]
	s_add_i32 m0, s11, 0xe000
	s_nop 0
	global_load_lds_dwordx4 v[196:197], off
	s_waitcnt vmcnt(8)
	s_waitcnt lgkmcnt(0)
	s_barrier
	s_waitcnt lgkmcnt(0)
	v_mfma_f32_16x16x32_bf16 v[180:183], v[60:63], v[140:143], v[180:183]
	v_mfma_f32_16x16x32_bf16 v[180:183], v[64:67], v[152:155], v[180:183]
	v_mfma_f32_16x16x32_bf16 v[176:179], v[68:71], v[140:143], v[176:179]
	v_mfma_f32_16x16x32_bf16 v[176:179], v[72:75], v[152:155], v[176:179]
	v_mfma_f32_16x16x32_bf16 v[148:151], v[60:63], v[156:159], v[148:151]
	v_mfma_f32_16x16x32_bf16 v[148:151], v[64:67], v[168:171], v[148:151]
	v_mfma_f32_16x16x32_bf16 v[144:147], v[68:71], v[156:159], v[144:147]
	v_mfma_f32_16x16x32_bf16 v[144:147], v[72:75], v[168:171], v[144:147]
	v_mfma_f32_16x16x32_bf16 v[124:127], v[60:63], v[172:175], v[124:127]
	v_mfma_f32_16x16x32_bf16 v[124:127], v[64:67], v[184:187], v[124:127]
	v_mfma_f32_16x16x32_bf16 v[120:123], v[68:71], v[172:175], v[120:123]
	v_mfma_f32_16x16x32_bf16 v[120:123], v[72:75], v[184:187], v[120:123]
	v_mfma_f32_16x16x32_bf16 v[96:99], v[60:63], v[188:191], v[96:99]
	v_mfma_f32_16x16x32_bf16 v[96:99], v[64:67], v[192:195], v[96:99]
	v_mfma_f32_16x16x32_bf16 v[92:95], v[68:71], v[188:191], v[92:95]
	v_mfma_f32_16x16x32_bf16 v[92:95], v[72:75], v[192:195], v[92:95]
	v_mfma_f32_16x16x32_bf16 v[164:167], v[100:103], v[140:143], v[164:167]
	v_mfma_f32_16x16x32_bf16 v[164:167], v[112:115], v[152:155], v[164:167]
	v_mfma_f32_16x16x32_bf16 v[132:135], v[100:103], v[156:159], v[132:135]
	v_mfma_f32_16x16x32_bf16 v[132:135], v[112:115], v[168:171], v[132:135]
	v_mfma_f32_16x16x32_bf16 v[128:131], v[116:119], v[156:159], v[128:131]
	v_mfma_f32_16x16x32_bf16 v[128:131], v[136:139], v[168:171], v[128:131]
	v_mfma_f32_16x16x32_bf16 v[108:111], v[100:103], v[172:175], v[108:111]
	v_mfma_f32_16x16x32_bf16 v[108:111], v[112:115], v[184:187], v[108:111]
	v_mfma_f32_16x16x32_bf16 v[104:107], v[116:119], v[172:175], v[104:107]
	v_mfma_f32_16x16x32_bf16 v[104:107], v[136:139], v[184:187], v[104:107]
	v_mfma_f32_16x16x32_bf16 v[88:91], v[100:103], v[188:191], v[88:91]
	v_mfma_f32_16x16x32_bf16 v[88:91], v[112:115], v[192:195], v[88:91]
	v_mfma_f32_16x16x32_bf16 v[84:87], v[116:119], v[188:191], v[84:87]
	v_mfma_f32_16x16x32_bf16 v[84:87], v[136:139], v[192:195], v[84:87]
	v_mfma_f32_16x16x32_bf16 v[140:143], v[116:119], v[140:143], v[160:163]
	v_mfma_f32_16x16x32_bf16 v[140:143], v[136:139], v[152:155], v[140:143]
	s_barrier
	s_add_i32 s16, s17, s67
	v_lshl_add_u64 v[200:201], s[22:23], 0, v[2:3]
	s_mov_b32 m0, s16
	ds_read_b128 v[152:155], v252 offset:16384
	ds_read_b128 v[156:159], v252 offset:17408
	ds_read_b128 v[160:163], v252 offset:18432
	ds_read_b128 v[168:171], v252 offset:19456
	ds_read_b128 v[172:175], v252 offset:20480
	ds_read_b128 v[184:187], v252 offset:21504
	ds_read_b128 v[188:191], v252 offset:22528
	ds_read_b128 v[192:195], v252 offset:23552
	global_load_lds_dwordx4 v[200:201], off
	s_add_i32 m0, s16, 0x2000
	s_add_u32 s78, s22, 0x20000
	v_lshl_add_u64 v[202:203], s[22:23], 0, v[210:211]
	s_addc_u32 s79, s23, 0
	s_add_i32 s15, s15, s67
	global_load_lds_dwordx4 v[202:203], off
	v_lshl_add_u64 v[196:197], s[78:79], 0, v[2:3]
	s_mov_b32 m0, s15
	v_lshl_add_u64 v[204:205], s[62:63], 0, v[214:215]
	global_load_lds_dwordx4 v[196:197], off
	v_lshl_add_u64 v[196:197], s[78:79], 0, v[210:211]
	s_add_i32 m0, s15, 0x2000
	v_lshl_add_u64 v[206:207], s[62:63], 0, v[212:213]
	global_load_lds_dwordx4 v[196:197], off
	s_mov_b32 m0, s11
	s_nop 0
	global_load_lds_dwordx4 v[204:205], off
	s_mov_b32 m0, s68
	s_nop 0
	global_load_lds_dwordx4 v[206:207], off
	s_waitcnt vmcnt(8)
	s_waitcnt lgkmcnt(0)
	s_barrier
; #define PG8_STAGE(bufoff, gbase, voff) do { _Pragma("unroll") for (int _i = 0; _i < 2; ++_i) \
;         __builtin_amdgcn_global_load_lds((const unsigned*)((const char*)(gbase) + (voff)[_i]), (PG8_LAS unsigned*)(lds + (bufoff) + ldsw + _i * 8192), 16, 0, 0); } while (0)
; #define PG8_LDA(dst, b, h) do { _Pragma("unroll") for (int m = 0; m < 4; ++m) _Pragma("unroll") for (int k = 0; k < 2; ++k) dst[m][k] = *(const PG8_LAS bf16x8*)(lds + PG8_SA(b, h) + aoff + m * 2048 + k * 1024); } while (0)
; #define PG8_LDB(dst, b, h) do { _Pragma("unroll") for (int n = 0; n < 2; ++n) _Pragma("unroll") for (int k = 0; k < 2; ++k) dst[n][k] = *(const PG8_LAS bf16x8*)(lds + PG8_SB(b, h) + boff + n * 2048 + k * 1024); } while (0)
; #define PG8_MMA(ai, bj, At, Bt) do { __builtin_amdgcn_s_setprio(1); _Pragma("unroll") for (int m = 0; m < 4; ++m) _Pragma("unroll") for (int n = 0; n < 2; ++n) _Pragma("unroll") for (int k = 0; k < 2; ++k) \
;         acc[ai][bj][m][n] = __builtin_amdgcn_mfma_f32_16x16x32_bf16(Bt[n][k], At[m][k], acc[ai][bj][m][n], 0, 0, 0); __builtin_amdgcn_s_setprio(0); } while (0)
; #define PG8_WAIT_V(n) asm volatile("s_waitcnt vmcnt(" #n ")" ::: "memory")
; #define PG8_WAIT_L(n) asm volatile("s_waitcnt lgkmcnt(" #n ")" ::: "memory")
; #define PG8_BAR __builtin_amdgcn_s_barrier()
; #define PG8_SCHED __builtin_amdgcn_sched_barrier(0)
; template <class Epi, class Sched, bool ALIGN_EPI = true>
; __device__ __forceinline__ void gemm_phase(PG8_LAS unsigned char* lds, const Gemm g, const Sched& S, const Epi& E, const int tid) {
;     ...
;             PG8_WAIT_V(8); PG8_WAIT_L(0); PG8_BAR; PG8_MMA(1, 0, At, B0); PG8_MMA(1, 1, At, B1); PG8_BAR; PG8_SCHED;
;             PG8_LDB(B0, 1, 0); PG8_LDB(B1, 1, 1); PG8_SCHED; PG8_LDA(At, 1, 0); PG8_STAGE(PG8_SA(0, 1), a2 + hstepA, voffA);
;             PG8_WAIT_V(8); PG8_WAIT_L(0); PG8_BAR; PG8_MMA(0, 0, At, B0); PG8_MMA(0, 1, At, B1); PG8_BAR; PG8_SCHED;
	s_waitcnt lgkmcnt(0)
	v_mfma_f32_16x16x32_bf16 v[80:83], v[60:63], v[152:155], v[80:83]
	v_mfma_f32_16x16x32_bf16 v[80:83], v[64:67], v[156:159], v[80:83]
	v_mfma_f32_16x16x32_bf16 v[76:79], v[68:71], v[152:155], v[76:79]
	v_mfma_f32_16x16x32_bf16 v[76:79], v[72:75], v[156:159], v[76:79]
	v_mfma_f32_16x16x32_bf16 v[48:51], v[60:63], v[160:163], v[48:51]
	v_mfma_f32_16x16x32_bf16 v[48:51], v[64:67], v[168:171], v[48:51]
	v_mfma_f32_16x16x32_bf16 v[44:47], v[68:71], v[160:163], v[44:47]
	v_mfma_f32_16x16x32_bf16 v[44:47], v[72:75], v[168:171], v[44:47]
	v_mfma_f32_16x16x32_bf16 v[32:35], v[60:63], v[172:175], v[32:35]
	v_mfma_f32_16x16x32_bf16 v[32:35], v[64:67], v[184:187], v[32:35]
	v_mfma_f32_16x16x32_bf16 v[28:31], v[68:71], v[172:175], v[28:31]
	v_mfma_f32_16x16x32_bf16 v[28:31], v[72:75], v[184:187], v[28:31]
	v_mfma_f32_16x16x32_bf16 v[16:19], v[60:63], v[188:191], v[16:19]
	v_mfma_f32_16x16x32_bf16 v[16:19], v[64:67], v[192:195], v[16:19]
	v_mfma_f32_16x16x32_bf16 v[12:15], v[68:71], v[188:191], v[12:15]
	v_mfma_f32_16x16x32_bf16 v[12:15], v[72:75], v[192:195], v[12:15]
	v_mfma_f32_16x16x32_bf16 v[56:59], v[100:103], v[152:155], v[56:59]
	v_mfma_f32_16x16x32_bf16 v[56:59], v[112:115], v[156:159], v[56:59]
	v_mfma_f32_16x16x32_bf16 v[52:55], v[116:119], v[152:155], v[52:55]
	v_mfma_f32_16x16x32_bf16 v[52:55], v[136:139], v[156:159], v[52:55]
	v_mfma_f32_16x16x32_bf16 v[40:43], v[100:103], v[160:163], v[40:43]
	v_mfma_f32_16x16x32_bf16 v[40:43], v[112:115], v[168:171], v[40:43]
	v_mfma_f32_16x16x32_bf16 v[36:39], v[116:119], v[160:163], v[36:39]
	v_mfma_f32_16x16x32_bf16 v[36:39], v[136:139], v[168:171], v[36:39]
	v_mfma_f32_16x16x32_bf16 v[24:27], v[100:103], v[172:175], v[24:27]
	v_mfma_f32_16x16x32_bf16 v[24:27], v[112:115], v[184:187], v[24:27]
	v_mfma_f32_16x16x32_bf16 v[20:23], v[116:119], v[172:175], v[20:23]
	v_mfma_f32_16x16x32_bf16 v[20:23], v[136:139], v[184:187], v[20:23]
	v_mfma_f32_16x16x32_bf16 v[8:11], v[100:103], v[188:191], v[8:11]
	v_mfma_f32_16x16x32_bf16 v[8:11], v[112:115], v[192:195], v[8:11]
	v_mfma_f32_16x16x32_bf16 v[4:7], v[116:119], v[188:191], v[4:7]
	v_mfma_f32_16x16x32_bf16 v[4:7], v[136:139], v[192:195], v[4:7]
	s_barrier
	s_add_i32 s15, 0, 0x18000
	s_add_i32 s16, 0, 0x1c000
	v_add_u32_e32 v72, s15, v251
	v_add_u32_e32 v136, s16, v251
	ds_read_b128 v[60:63], v72
	ds_read_b128 v[64:67], v72 offset:1024
	ds_read_b128 v[68:71], v72 offset:2048
	ds_read_b128 v[72:75], v72 offset:3072
	ds_read_b128 v[100:103], v136
	ds_read_b128 v[112:115], v136 offset:1024
	ds_read_b128 v[116:119], v136 offset:2048
	ds_read_b128 v[136:139], v136 offset:3072
	s_add_u32 s62, s62, 0x80000
	s_addc_u32 s63, s63, 0
	s_mov_b32 m0, s69
	v_lshl_add_u64 v[160:161], s[62:63], 0, v[214:215]
	ds_read_b128 v[152:155], v252 offset:32768
	ds_read_b128 v[156:159], v252 offset:33792
	ds_read_b128 v[168:171], v252 offset:34816
	ds_read_b128 v[172:175], v252 offset:35840
	ds_read_b128 v[184:187], v252 offset:36864
	ds_read_b128 v[188:191], v252 offset:37888
	ds_read_b128 v[192:195], v252 offset:38912
	ds_read_b128 v[196:199], v252 offset:39936
	global_load_lds_dwordx4 v[160:161], off
	v_lshl_add_u64 v[160:161], s[62:63], 0, v[212:213]
	s_mov_b32 m0, s70
	s_nop 0
	global_load_lds_dwordx4 v[160:161], off
	s_waitcnt vmcnt(8)
	s_waitcnt lgkmcnt(0)
	s_barrier
	s_waitcnt lgkmcnt(0)
	v_mfma_f32_16x16x32_bf16 v[160:163], v[60:63], v[152:155], v[180:183]
	v_mfma_f32_16x16x32_bf16 v[180:183], v[64:67], v[156:159], v[160:163]
	v_mfma_f32_16x16x32_bf16 v[160:163], v[68:71], v[152:155], v[176:179]
	v_mfma_f32_16x16x32_bf16 v[176:179], v[72:75], v[156:159], v[160:163]
	v_mfma_f32_16x16x32_bf16 v[148:151], v[60:63], v[168:171], v[148:151]
	v_mfma_f32_16x16x32_bf16 v[148:151], v[64:67], v[172:175], v[148:151]
	v_mfma_f32_16x16x32_bf16 v[144:147], v[68:71], v[168:171], v[144:147]
	v_mfma_f32_16x16x32_bf16 v[144:147], v[72:75], v[172:175], v[144:147]
	v_mfma_f32_16x16x32_bf16 v[124:127], v[60:63], v[184:187], v[124:127]
	v_mfma_f32_16x16x32_bf16 v[124:127], v[64:67], v[188:191], v[124:127]
	v_mfma_f32_16x16x32_bf16 v[120:123], v[68:71], v[184:187], v[120:123]
	v_mfma_f32_16x16x32_bf16 v[120:123], v[72:75], v[188:191], v[120:123]
	v_mfma_f32_16x16x32_bf16 v[96:99], v[60:63], v[192:195], v[96:99]
	v_mfma_f32_16x16x32_bf16 v[96:99], v[64:67], v[196:199], v[96:99]
	v_mfma_f32_16x16x32_bf16 v[92:95], v[68:71], v[192:195], v[92:95]
	v_mfma_f32_16x16x32_bf16 v[92:95], v[72:75], v[196:199], v[92:95]
	v_mfma_f32_16x16x32_bf16 v[160:163], v[100:103], v[152:155], v[164:167]
	v_mfma_f32_16x16x32_bf16 v[164:167], v[112:115], v[156:159], v[160:163]
	v_mfma_f32_16x16x32_bf16 v[140:143], v[116:119], v[152:155], v[140:143]
	v_mfma_f32_16x16x32_bf16 v[160:163], v[136:139], v[156:159], v[140:143]
	v_mfma_f32_16x16x32_bf16 v[132:135], v[100:103], v[168:171], v[132:135]
	v_mfma_f32_16x16x32_bf16 v[132:135], v[112:115], v[172:175], v[132:135]
	v_mfma_f32_16x16x32_bf16 v[128:131], v[116:119], v[168:171], v[128:131]
	v_mfma_f32_16x16x32_bf16 v[128:131], v[136:139], v[172:175], v[128:131]
	v_mfma_f32_16x16x32_bf16 v[108:111], v[100:103], v[184:187], v[108:111]
	v_mfma_f32_16x16x32_bf16 v[108:111], v[112:115], v[188:191], v[108:111]
	v_mfma_f32_16x16x32_bf16 v[104:107], v[116:119], v[184:187], v[104:107]
	v_mfma_f32_16x16x32_bf16 v[104:107], v[136:139], v[188:191], v[104:107]
	v_mfma_f32_16x16x32_bf16 v[88:91], v[100:103], v[192:195], v[88:91]
	v_mfma_f32_16x16x32_bf16 v[88:91], v[112:115], v[196:199], v[88:91]
	v_mfma_f32_16x16x32_bf16 v[84:87], v[116:119], v[192:195], v[84:87]
	v_mfma_f32_16x16x32_bf16 v[84:87], v[136:139], v[196:199], v[84:87]
	s_barrier
; #define PG8_STAGE(bufoff, gbase, voff) do { _Pragma("unroll") for (int _i = 0; _i < 2; ++_i) \
;         __builtin_amdgcn_global_load_lds((const unsigned*)((const char*)(gbase) + (voff)[_i]), (PG8_LAS unsigned*)(lds + (bufoff) + ldsw + _i * 8192), 16, 0, 0); } while (0)
; #define PG8_LDA(dst, b, h) do { _Pragma("unroll") for (int m = 0; m < 4; ++m) _Pragma("unroll") for (int k = 0; k < 2; ++k) dst[m][k] = *(const PG8_LAS bf16x8*)(lds + PG8_SA(b, h) + aoff + m * 2048 + k * 1024); } while (0)
; #define PG8_MMA(ai, bj, At, Bt) do { __builtin_amdgcn_s_setprio(1); _Pragma("unroll") for (int m = 0; m < 4; ++m) _Pragma("unroll") for (int n = 0; n < 2; ++n) _Pragma("unroll") for (int k = 0; k < 2; ++k) \
;         acc[ai][bj][m][n] = __builtin_amdgcn_mfma_f32_16x16x32_bf16(Bt[n][k], At[m][k], acc[ai][bj][m][n], 0, 0, 0); __builtin_amdgcn_s_setprio(0); } while (0)
; #define PG8_WAIT_V(n) asm volatile("s_waitcnt vmcnt(" #n ")" ::: "memory")
; #define PG8_WAIT_L(n) asm volatile("s_waitcnt lgkmcnt(" #n ")" ::: "memory")
; #define PG8_BAR __builtin_amdgcn_s_barrier()
; #define PG8_SCHED __builtin_amdgcn_sched_barrier(0)
; template <class Epi, class Sched, bool ALIGN_EPI = true>
; __device__ __forceinline__ void gemm_phase(PG8_LAS unsigned char* lds, const Gemm g, const Sched& S, const Epi& E, const int tid) {
;     ...
;             PG8_LDA(At, 1, 1); PG8_STAGE(PG8_SB(1, 0), b3, voffB); PG8_STAGE(PG8_SB(1, 1), b3 + hstepB, voffB); PG8_STAGE(PG8_SA(1, 0), a3, voffA);
;             PG8_WAIT_V(8); PG8_WAIT_L(0); PG8_BAR; PG8_MMA(1, 0, At, B0); PG8_MMA(1, 1, At, B1); PG8_BAR; PG8_SCHED;
;         }
;         if constexpr (ALIGN_EPI) { if (wr == 0) PG8_BAR; }
	s_add_i32 s15, s15, s67
	v_lshl_add_u64 v[196:197], v[200:201], 0, s[36:37]
	s_mov_b32 m0, s15
	ds_read_b128 v[140:143], v252 offset:49152
	ds_read_b128 v[152:155], v252 offset:50176
	ds_read_b128 v[156:159], v252 offset:51200
	ds_read_b128 v[168:171], v252 offset:52224
	ds_read_b128 v[172:175], v252 offset:53248
	ds_read_b128 v[184:187], v252 offset:54272
	ds_read_b128 v[188:191], v252 offset:55296
	ds_read_b128 v[192:195], v252 offset:56320
	global_load_lds_dwordx4 v[196:197], off
	s_add_i32 m0, s15, 0x2000
	s_add_u32 s22, s22, 0x20080
	v_lshl_add_u64 v[196:197], v[202:203], 0, s[36:37]
	s_addc_u32 s23, s23, 0
	s_add_i32 s15, s16, s67
	global_load_lds_dwordx4 v[196:197], off
	v_lshl_add_u64 v[196:197], s[22:23], 0, v[2:3]
	s_mov_b32 m0, s15
	s_nop 0
	global_load_lds_dwordx4 v[196:197], off
	v_lshl_add_u64 v[196:197], s[22:23], 0, v[210:211]
	s_add_i32 m0, s15, 0x2000
	s_nop 0
	global_load_lds_dwordx4 v[196:197], off
	v_lshl_add_u64 v[196:197], v[204:205], 0, s[36:37]
	s_mov_b32 m0, s75
	s_nop 0
	global_load_lds_dwordx4 v[196:197], off
	v_lshl_add_u64 v[196:197], v[206:207], 0, s[36:37]
	s_mov_b32 m0, s76
	s_nop 0
	global_load_lds_dwordx4 v[196:197], off
	s_waitcnt vmcnt(8)
	s_waitcnt lgkmcnt(0)
	s_barrier
	s_waitcnt lgkmcnt(0)
	v_mfma_f32_16x16x32_bf16 v[80:83], v[60:63], v[140:143], v[80:83]
	v_mfma_f32_16x16x32_bf16 v[80:83], v[64:67], v[152:155], v[80:83]
	v_mfma_f32_16x16x32_bf16 v[76:79], v[68:71], v[140:143], v[76:79]
	v_mfma_f32_16x16x32_bf16 v[76:79], v[72:75], v[152:155], v[76:79]
	v_mfma_f32_16x16x32_bf16 v[48:51], v[60:63], v[156:159], v[48:51]
	v_mfma_f32_16x16x32_bf16 v[48:51], v[64:67], v[168:171], v[48:51]
	v_mfma_f32_16x16x32_bf16 v[44:47], v[68:71], v[156:159], v[44:47]
	v_mfma_f32_16x16x32_bf16 v[44:47], v[72:75], v[168:171], v[44:47]
	v_mfma_f32_16x16x32_bf16 v[32:35], v[60:63], v[172:175], v[32:35]
	v_mfma_f32_16x16x32_bf16 v[32:35], v[64:67], v[184:187], v[32:35]
	v_mfma_f32_16x16x32_bf16 v[28:31], v[68:71], v[172:175], v[28:31]
	v_mfma_f32_16x16x32_bf16 v[28:31], v[72:75], v[184:187], v[28:31]
	v_mfma_f32_16x16x32_bf16 v[16:19], v[60:63], v[188:191], v[16:19]
	v_mfma_f32_16x16x32_bf16 v[16:19], v[64:67], v[192:195], v[16:19]
	v_mfma_f32_16x16x32_bf16 v[12:15], v[68:71], v[188:191], v[12:15]
	v_mfma_f32_16x16x32_bf16 v[12:15], v[72:75], v[192:195], v[12:15]
	v_mfma_f32_16x16x32_bf16 v[56:59], v[100:103], v[140:143], v[56:59]
	v_mfma_f32_16x16x32_bf16 v[56:59], v[112:115], v[152:155], v[56:59]
	v_mfma_f32_16x16x32_bf16 v[52:55], v[116:119], v[140:143], v[52:55]
	v_mfma_f32_16x16x32_bf16 v[52:55], v[136:139], v[152:155], v[52:55]
	v_mfma_f32_16x16x32_bf16 v[40:43], v[100:103], v[156:159], v[40:43]
	v_mfma_f32_16x16x32_bf16 v[40:43], v[112:115], v[168:171], v[40:43]
	v_mfma_f32_16x16x32_bf16 v[36:39], v[116:119], v[156:159], v[36:39]
	v_mfma_f32_16x16x32_bf16 v[36:39], v[136:139], v[168:171], v[36:39]
	v_mfma_f32_16x16x32_bf16 v[24:27], v[100:103], v[172:175], v[24:27]
	v_mfma_f32_16x16x32_bf16 v[24:27], v[112:115], v[184:187], v[24:27]
	v_mfma_f32_16x16x32_bf16 v[20:23], v[116:119], v[172:175], v[20:23]
	v_mfma_f32_16x16x32_bf16 v[20:23], v[136:139], v[184:187], v[20:23]
	v_mfma_f32_16x16x32_bf16 v[8:11], v[100:103], v[188:191], v[8:11]
	v_mfma_f32_16x16x32_bf16 v[8:11], v[112:115], v[192:195], v[8:11]
	v_mfma_f32_16x16x32_bf16 v[4:7], v[116:119], v[188:191], v[4:7]
	v_mfma_f32_16x16x32_bf16 v[4:7], v[136:139], v[192:195], v[4:7]
	s_barrier
	s_add_i32 s53, s53, 2
	s_add_u32 s12, s12, 0x100
	s_addc_u32 s13, s13, 0
	s_add_u32 s20, s20, 0x100
	s_addc_u32 s21, s21, 0
	s_cmp_gt_u32 s53, 5
	s_cbranch_scc0 .LBB0_426
	s_and_b64 vcc, exec, s[48:49]
	s_cbranch_vccz .LBB0_429
	s_barrier

; #define PG8_STAGE(bufoff, gbase, voff) do { _Pragma("unroll") for (int _i = 0; _i < 2; ++_i) \
;         __builtin_amdgcn_global_load_lds((const unsigned*)((const char*)(gbase) + (voff)[_i]), (PG8_LAS unsigned*)(lds + (bufoff) + ldsw + _i * 8192), 16, 0, 0); } while (0)
; #define PG8_LDA(dst, b, h) do { _Pragma("unroll") for (int m = 0; m < 4; ++m) _Pragma("unroll") for (int k = 0; k < 2; ++k) dst[m][k] = *(const PG8_LAS bf16x8*)(lds + PG8_SA(b, h) + aoff + m * 2048 + k * 1024); } while (0)
; #define PG8_LDB(dst, b, h) do { _Pragma("unroll") for (int n = 0; n < 2; ++n) _Pragma("unroll") for (int k = 0; k < 2; ++k) dst[n][k] = *(const PG8_LAS bf16x8*)(lds + PG8_SB(b, h) + boff + n * 2048 + k * 1024); } while (0)
; #define PG8_MMA(ai, bj, At, Bt) do { __builtin_amdgcn_s_setprio(1); _Pragma("unroll") for (int m = 0; m < 4; ++m) _Pragma("unroll") for (int n = 0; n < 2; ++n) _Pragma("unroll") for (int k = 0; k < 2; ++k) \
;         acc[ai][bj][m][n] = __builtin_amdgcn_mfma_f32_16x16x32_bf16(Bt[n][k], At[m][k], acc[ai][bj][m][n], 0, 0, 0); __builtin_amdgcn_s_setprio(0); } while (0)
; #define PG8_WAIT_V(n) asm volatile("s_waitcnt vmcnt(" #n ")" ::: "memory")
; #define PG8_WAIT_L(n) asm volatile("s_waitcnt lgkmcnt(" #n ")" ::: "memory")
; template <class Epi, class Sched, bool ALIGN_EPI = true>
; __device__ __forceinline__ void gemm_phase(PG8_LAS unsigned char* lds, const Gemm g, const Sched& S, const Epi& E, const int tid) {
;     ...
;         for (int t = 0; t < nt; t += 2) {
;             const bool last = (t == nt - 2);
;             const char* a1 = cA + (size_t)(t + 1) * kstep;
;             const char* a2 = last ? nA : cA + (size_t)(t + 2) * kstep; const char* b2 = last ? nB : cB + (size_t)(t + 2) * kstep;
;             const char* a3 = a2 + kstep; const char* b3 = b2 + kstep;
;             if (last && has_next) S.a_ready(nxt);
;             PG8_LDB(B0, 0, 0); PG8_LDB(B1, 0, 1); PG8_SCHED; PG8_LDA(At, 0, 0); PG8_STAGE(PG8_SA(1, 1), a1 + hstepA, voffA);
;             PG8_WAIT_V(8); PG8_WAIT_L(0); PG8_BAR; PG8_MMA(0, 0, At, B0); PG8_MMA(0, 1, At, B1); PG8_BAR; PG8_SCHED;
;             PG8_LDA(At, 0, 1); PG8_STAGE(PG8_SB(0, 0), b2, voffB); PG8_STAGE(PG8_SB(0, 1), b2 + hstepB, voffB); PG8_STAGE(PG8_SA(0, 0), a2, voffA);
;             PG8_WAIT_V(8); PG8_WAIT_L(0); PG8_BAR; PG8_MMA(1, 0, At, B0); PG8_MMA(1, 1, At, B1); PG8_BAR; PG8_SCHED;
.LBB0_1087:
	s_add_i32 s45, s22, 2
	s_add_u32 s15, s12, 0xfff80080
	s_addc_u32 s16, s13, -1
	s_add_i32 s17, 0, 0x10000
	s_cmp_eq_u32 s1, s22
	s_cselect_b32 s55, s51, s16
	s_cselect_b32 s54, s50, s15
	s_cselect_b32 s23, s53, s21
	s_cselect_b32 s22, s52, s20
	s_add_i32 s15, 0, 0x14000
	v_add_u32_e32 v72, s17, v251
	v_add_u32_e32 v128, s15, v251
	ds_read_b128 v[56:59], v72
	ds_read_b128 v[64:67], v72 offset:1024
	ds_read_b128 v[68:71], v72 offset:2048
	ds_read_b128 v[72:75], v72 offset:3072
	ds_read_b128 v[92:95], v128
	ds_read_b128 v[104:107], v128 offset:1024
	ds_read_b128 v[116:119], v128 offset:2048
	ds_read_b128 v[128:131], v128 offset:3072
	v_lshl_add_u64 v[196:197], s[12:13], 0, v[216:217]
	s_add_i32 m0, s11, 0xc000
	ds_read_b128 v[140:143], v252
	ds_read_b128 v[152:155], v252 offset:1024
	ds_read_b128 v[156:159], v252 offset:2048
	ds_read_b128 v[160:163], v252 offset:3072
	ds_read_b128 v[172:175], v252 offset:4096
	ds_read_b128 v[184:187], v252 offset:5120
	ds_read_b128 v[188:191], v252 offset:6144
	ds_read_b128 v[192:195], v252 offset:7168
	global_load_lds_dwordx4 v[196:197], off
	v_lshl_add_u64 v[196:197], s[12:13], 0, v[218:219]
	s_add_i32 m0, s11, 0xe000
	s_nop 0
	global_load_lds_dwordx4 v[196:197], off
	s_waitcnt vmcnt(8)
	s_waitcnt lgkmcnt(0)
	s_barrier
	s_waitcnt lgkmcnt(0)
	v_mfma_f32_16x16x32_bf16 v[180:183], v[56:59], v[140:143], v[180:183]
	v_mfma_f32_16x16x32_bf16 v[180:183], v[64:67], v[152:155], v[180:183]
	v_mfma_f32_16x16x32_bf16 v[176:179], v[68:71], v[140:143], v[176:179]
	v_mfma_f32_16x16x32_bf16 v[176:179], v[72:75], v[152:155], v[176:179]
	v_mfma_f32_16x16x32_bf16 v[148:151], v[56:59], v[156:159], v[148:151]
	v_mfma_f32_16x16x32_bf16 v[148:151], v[64:67], v[160:163], v[148:151]
	v_mfma_f32_16x16x32_bf16 v[144:147], v[68:71], v[156:159], v[144:147]
	v_mfma_f32_16x16x32_bf16 v[144:147], v[72:75], v[160:163], v[144:147]
	v_mfma_f32_16x16x32_bf16 v[124:127], v[56:59], v[172:175], v[124:127]
	v_mfma_f32_16x16x32_bf16 v[124:127], v[64:67], v[184:187], v[124:127]
	v_mfma_f32_16x16x32_bf16 v[120:123], v[68:71], v[172:175], v[120:123]
	v_mfma_f32_16x16x32_bf16 v[120:123], v[72:75], v[184:187], v[120:123]
	v_mfma_f32_16x16x32_bf16 v[100:103], v[56:59], v[188:191], v[100:103]
	v_mfma_f32_16x16x32_bf16 v[100:103], v[64:67], v[192:195], v[100:103]
	v_mfma_f32_16x16x32_bf16 v[96:99], v[68:71], v[188:191], v[96:99]
	v_mfma_f32_16x16x32_bf16 v[96:99], v[72:75], v[192:195], v[96:99]
	v_mfma_f32_16x16x32_bf16 v[168:171], v[92:95], v[140:143], v[168:171]
	v_mfma_f32_16x16x32_bf16 v[168:171], v[104:107], v[152:155], v[168:171]
	v_mfma_f32_16x16x32_bf16 v[136:139], v[92:95], v[156:159], v[136:139]
	v_mfma_f32_16x16x32_bf16 v[136:139], v[104:107], v[160:163], v[136:139]
	v_mfma_f32_16x16x32_bf16 v[132:135], v[116:119], v[156:159], v[132:135]
	v_mfma_f32_16x16x32_bf16 v[132:135], v[128:131], v[160:163], v[132:135]
	v_mfma_f32_16x16x32_bf16 v[112:115], v[92:95], v[172:175], v[112:115]
	v_mfma_f32_16x16x32_bf16 v[112:115], v[104:107], v[184:187], v[112:115]
	v_mfma_f32_16x16x32_bf16 v[108:111], v[116:119], v[172:175], v[108:111]
	v_mfma_f32_16x16x32_bf16 v[108:111], v[128:131], v[184:187], v[108:111]
	v_mfma_f32_16x16x32_bf16 v[88:91], v[92:95], v[188:191], v[88:91]
	v_mfma_f32_16x16x32_bf16 v[88:91], v[104:107], v[192:195], v[88:91]
	v_mfma_f32_16x16x32_bf16 v[84:87], v[116:119], v[188:191], v[84:87]
	v_mfma_f32_16x16x32_bf16 v[84:87], v[128:131], v[192:195], v[84:87]
	v_mfma_f32_16x16x32_bf16 v[140:143], v[116:119], v[140:143], v[164:167]
	v_mfma_f32_16x16x32_bf16 v[140:143], v[128:131], v[152:155], v[140:143]
	s_barrier
	s_add_i32 s16, s17, s60
	v_lshl_add_u64 v[200:201], s[22:23], 0, v[2:3]
	s_mov_b32 m0, s16
	ds_read_b128 v[152:155], v252 offset:16384
	ds_read_b128 v[156:159], v252 offset:17408
	ds_read_b128 v[160:163], v252 offset:18432
	ds_read_b128 v[164:167], v252 offset:19456
	ds_read_b128 v[172:175], v252 offset:20480
	ds_read_b128 v[184:187], v252 offset:21504
	ds_read_b128 v[188:191], v252 offset:22528
	ds_read_b128 v[192:195], v252 offset:23552
	global_load_lds_dwordx4 v[200:201], off
	s_add_i32 m0, s16, 0x2000
	s_add_u32 s72, s22, 0x80000
	v_lshl_add_u64 v[202:203], s[22:23], 0, v[214:215]
	s_addc_u32 s73, s23, 0
	s_add_i32 s15, s15, s60
	global_load_lds_dwordx4 v[202:203], off
	v_lshl_add_u64 v[196:197], s[72:73], 0, v[2:3]
	s_mov_b32 m0, s15
	v_lshl_add_u64 v[204:205], s[54:55], 0, v[210:211]
	global_load_lds_dwordx4 v[196:197], off
	v_lshl_add_u64 v[196:197], s[72:73], 0, v[214:215]
	s_add_i32 m0, s15, 0x2000
	v_lshl_add_u64 v[206:207], s[54:55], 0, v[212:213]
	global_load_lds_dwordx4 v[196:197], off
	s_mov_b32 m0, s11
	s_nop 0
	global_load_lds_dwordx4 v[204:205], off
	s_mov_b32 m0, s61
	s_nop 0
	global_load_lds_dwordx4 v[206:207], off
	s_waitcnt vmcnt(8)
	s_waitcnt lgkmcnt(0)
	s_barrier
; #define PG8_STAGE(bufoff, gbase, voff) do { _Pragma("unroll") for (int _i = 0; _i < 2; ++_i) \
;         __builtin_amdgcn_global_load_lds((const unsigned*)((const char*)(gbase) + (voff)[_i]), (PG8_LAS unsigned*)(lds + (bufoff) + ldsw + _i * 8192), 16, 0, 0); } while (0)
; #define PG8_LDA(dst, b, h) do { _Pragma("unroll") for (int m = 0; m < 4; ++m) _Pragma("unroll") for (int k = 0; k < 2; ++k) dst[m][k] = *(const PG8_LAS bf16x8*)(lds + PG8_SA(b, h) + aoff + m * 2048 + k * 1024); } while (0)
; #define PG8_LDB(dst, b, h) do { _Pragma("unroll") for (int n = 0; n < 2; ++n) _Pragma("unroll") for (int k = 0; k < 2; ++k) dst[n][k] = *(const PG8_LAS bf16x8*)(lds + PG8_SB(b, h) + boff + n * 2048 + k * 1024); } while (0)
; #define PG8_MMA(ai, bj, At, Bt) do { __builtin_amdgcn_s_setprio(1); _Pragma("unroll") for (int m = 0; m < 4; ++m) _Pragma("unroll") for (int n = 0; n < 2; ++n) _Pragma("unroll") for (int k = 0; k < 2; ++k) \
;         acc[ai][bj][m][n] = __builtin_amdgcn_mfma_f32_16x16x32_bf16(Bt[n][k], At[m][k], acc[ai][bj][m][n], 0, 0, 0); __builtin_amdgcn_s_setprio(0); } while (0)
; #define PG8_WAIT_V(n) asm volatile("s_waitcnt vmcnt(" #n ")" ::: "memory")
; #define PG8_WAIT_L(n) asm volatile("s_waitcnt lgkmcnt(" #n ")" ::: "memory")
; #define PG8_BAR __builtin_amdgcn_s_barrier()
; #define PG8_SCHED __builtin_amdgcn_sched_barrier(0)
; template <class Epi, class Sched, bool ALIGN_EPI = true>
; __device__ __forceinline__ void gemm_phase(PG8_LAS unsigned char* lds, const Gemm g, const Sched& S, const Epi& E, const int tid) {
;     ...
;             PG8_WAIT_V(8); PG8_WAIT_L(0); PG8_BAR; PG8_MMA(1, 0, At, B0); PG8_MMA(1, 1, At, B1); PG8_BAR; PG8_SCHED;
;             PG8_LDB(B0, 1, 0); PG8_LDB(B1, 1, 1); PG8_SCHED; PG8_LDA(At, 1, 0); PG8_STAGE(PG8_SA(0, 1), a2 + hstepA, voffA);
;             PG8_WAIT_V(8); PG8_WAIT_L(0); PG8_BAR; PG8_MMA(0, 0, At, B0); PG8_MMA(0, 1, At, B1); PG8_BAR; PG8_SCHED;
	s_waitcnt lgkmcnt(0)
	v_mfma_f32_16x16x32_bf16 v[80:83], v[56:59], v[152:155], v[80:83]
	v_mfma_f32_16x16x32_bf16 v[80:83], v[64:67], v[156:159], v[80:83]
	v_mfma_f32_16x16x32_bf16 v[76:79], v[68:71], v[152:155], v[76:79]
	v_mfma_f32_16x16x32_bf16 v[76:79], v[72:75], v[156:159], v[76:79]
	v_mfma_f32_16x16x32_bf16 v[48:51], v[56:59], v[160:163], v[48:51]
	v_mfma_f32_16x16x32_bf16 v[48:51], v[64:67], v[164:167], v[48:51]
	v_mfma_f32_16x16x32_bf16 v[44:47], v[68:71], v[160:163], v[44:47]
	v_mfma_f32_16x16x32_bf16 v[44:47], v[72:75], v[164:167], v[44:47]
	v_mfma_f32_16x16x32_bf16 v[32:35], v[56:59], v[172:175], v[32:35]
	v_mfma_f32_16x16x32_bf16 v[32:35], v[64:67], v[184:187], v[32:35]
	v_mfma_f32_16x16x32_bf16 v[28:31], v[68:71], v[172:175], v[28:31]
	v_mfma_f32_16x16x32_bf16 v[28:31], v[72:75], v[184:187], v[28:31]
	v_mfma_f32_16x16x32_bf16 v[16:19], v[56:59], v[188:191], v[16:19]
	v_mfma_f32_16x16x32_bf16 v[16:19], v[64:67], v[192:195], v[16:19]
	v_mfma_f32_16x16x32_bf16 v[12:15], v[68:71], v[188:191], v[12:15]
	v_mfma_f32_16x16x32_bf16 v[12:15], v[72:75], v[192:195], v[12:15]
	v_mfma_f32_16x16x32_bf16 v[52:55], v[116:119], v[152:155], v[52:55]
	v_mfma_f32_16x16x32_bf16 v[52:55], v[128:131], v[156:159], v[52:55]
	v_mfma_f32_16x16x32_bf16 v[40:43], v[92:95], v[160:163], v[40:43]
	v_mfma_f32_16x16x32_bf16 v[40:43], v[104:107], v[164:167], v[40:43]
	v_mfma_f32_16x16x32_bf16 v[36:39], v[116:119], v[160:163], v[36:39]
	v_mfma_f32_16x16x32_bf16 v[36:39], v[128:131], v[164:167], v[36:39]
	v_mfma_f32_16x16x32_bf16 v[24:27], v[92:95], v[172:175], v[24:27]
	v_mfma_f32_16x16x32_bf16 v[24:27], v[104:107], v[184:187], v[24:27]
	v_mfma_f32_16x16x32_bf16 v[20:23], v[116:119], v[172:175], v[20:23]
	v_mfma_f32_16x16x32_bf16 v[20:23], v[128:131], v[184:187], v[20:23]
	v_mfma_f32_16x16x32_bf16 v[8:11], v[92:95], v[188:191], v[8:11]
	v_mfma_f32_16x16x32_bf16 v[8:11], v[104:107], v[192:195], v[8:11]
	v_mfma_f32_16x16x32_bf16 v[4:7], v[116:119], v[188:191], v[4:7]
	v_mfma_f32_16x16x32_bf16 v[4:7], v[128:131], v[192:195], v[4:7]
	v_mfma_f32_16x16x32_bf16 v[56:59], v[92:95], v[152:155], v[60:63]
	v_mfma_f32_16x16x32_bf16 v[56:59], v[104:107], v[156:159], v[56:59]
	s_barrier
	s_add_i32 s15, 0, 0x18000
	s_add_i32 s16, 0, 0x1c000
	v_add_u32_e32 v72, s15, v251
	v_add_u32_e32 v128, s16, v251
	ds_read_b128 v[60:63], v72
	ds_read_b128 v[64:67], v72 offset:1024
	ds_read_b128 v[68:71], v72 offset:2048
	ds_read_b128 v[72:75], v72 offset:3072
	ds_read_b128 v[92:95], v128
	ds_read_b128 v[104:107], v128 offset:1024
	ds_read_b128 v[116:119], v128 offset:2048
	ds_read_b128 v[128:131], v128 offset:3072
	s_add_u32 s54, s54, 0x80000
	s_addc_u32 s55, s55, 0
	s_mov_b32 m0, s62
	v_lshl_add_u64 v[164:165], s[54:55], 0, v[210:211]
	ds_read_b128 v[152:155], v252 offset:32768
	ds_read_b128 v[156:159], v252 offset:33792
	ds_read_b128 v[160:163], v252 offset:34816
	ds_read_b128 v[172:175], v252 offset:35840
	ds_read_b128 v[184:187], v252 offset:36864
	ds_read_b128 v[188:191], v252 offset:37888
	ds_read_b128 v[192:195], v252 offset:38912
	ds_read_b128 v[196:199], v252 offset:39936
	global_load_lds_dwordx4 v[164:165], off
	v_lshl_add_u64 v[164:165], s[54:55], 0, v[212:213]
	s_mov_b32 m0, s63
	s_nop 0
	global_load_lds_dwordx4 v[164:165], off
	s_waitcnt vmcnt(8)
	s_waitcnt lgkmcnt(0)
	s_barrier
	s_waitcnt lgkmcnt(0)
	v_mfma_f32_16x16x32_bf16 v[164:167], v[60:63], v[152:155], v[180:183]
	v_mfma_f32_16x16x32_bf16 v[180:183], v[64:67], v[156:159], v[164:167]
	v_mfma_f32_16x16x32_bf16 v[164:167], v[68:71], v[152:155], v[176:179]
	v_mfma_f32_16x16x32_bf16 v[176:179], v[72:75], v[156:159], v[164:167]
	v_mfma_f32_16x16x32_bf16 v[148:151], v[60:63], v[160:163], v[148:151]
	v_mfma_f32_16x16x32_bf16 v[148:151], v[64:67], v[172:175], v[148:151]
	v_mfma_f32_16x16x32_bf16 v[144:147], v[68:71], v[160:163], v[144:147]
	v_mfma_f32_16x16x32_bf16 v[144:147], v[72:75], v[172:175], v[144:147]
	v_mfma_f32_16x16x32_bf16 v[124:127], v[60:63], v[184:187], v[124:127]
	v_mfma_f32_16x16x32_bf16 v[124:127], v[64:67], v[188:191], v[124:127]
	v_mfma_f32_16x16x32_bf16 v[120:123], v[68:71], v[184:187], v[120:123]
	v_mfma_f32_16x16x32_bf16 v[120:123], v[72:75], v[188:191], v[120:123]
	v_mfma_f32_16x16x32_bf16 v[100:103], v[60:63], v[192:195], v[100:103]
	v_mfma_f32_16x16x32_bf16 v[100:103], v[64:67], v[196:199], v[100:103]
	v_mfma_f32_16x16x32_bf16 v[96:99], v[68:71], v[192:195], v[96:99]
	v_mfma_f32_16x16x32_bf16 v[96:99], v[72:75], v[196:199], v[96:99]
	v_mfma_f32_16x16x32_bf16 v[164:167], v[92:95], v[152:155], v[168:171]
	v_mfma_f32_16x16x32_bf16 v[168:171], v[104:107], v[156:159], v[164:167]
	v_mfma_f32_16x16x32_bf16 v[140:143], v[116:119], v[152:155], v[140:143]
	v_mfma_f32_16x16x32_bf16 v[164:167], v[128:131], v[156:159], v[140:143]
	v_mfma_f32_16x16x32_bf16 v[136:139], v[92:95], v[160:163], v[136:139]
	v_mfma_f32_16x16x32_bf16 v[136:139], v[104:107], v[172:175], v[136:139]
	v_mfma_f32_16x16x32_bf16 v[132:135], v[116:119], v[160:163], v[132:135]
	v_mfma_f32_16x16x32_bf16 v[132:135], v[128:131], v[172:175], v[132:135]
	v_mfma_f32_16x16x32_bf16 v[112:115], v[92:95], v[184:187], v[112:115]
	v_mfma_f32_16x16x32_bf16 v[112:115], v[104:107], v[188:191], v[112:115]
	v_mfma_f32_16x16x32_bf16 v[108:111], v[116:119], v[184:187], v[108:111]
	v_mfma_f32_16x16x32_bf16 v[108:111], v[128:131], v[188:191], v[108:111]
	v_mfma_f32_16x16x32_bf16 v[88:91], v[92:95], v[192:195], v[88:91]
	v_mfma_f32_16x16x32_bf16 v[88:91], v[104:107], v[196:199], v[88:91]
	v_mfma_f32_16x16x32_bf16 v[84:87], v[116:119], v[192:195], v[84:87]
	v_mfma_f32_16x16x32_bf16 v[84:87], v[128:131], v[196:199], v[84:87]
	s_barrier
; #define PG8_STAGE(bufoff, gbase, voff) do { _Pragma("unroll") for (int _i = 0; _i < 2; ++_i) \
;         __builtin_amdgcn_global_load_lds((const unsigned*)((const char*)(gbase) + (voff)[_i]), (PG8_LAS unsigned*)(lds + (bufoff) + ldsw + _i * 8192), 16, 0, 0); } while (0)
; #define PG8_LDA(dst, b, h) do { _Pragma("unroll") for (int m = 0; m < 4; ++m) _Pragma("unroll") for (int k = 0; k < 2; ++k) dst[m][k] = *(const PG8_LAS bf16x8*)(lds + PG8_SA(b, h) + aoff + m * 2048 + k * 1024); } while (0)
; #define PG8_MMA(ai, bj, At, Bt) do { __builtin_amdgcn_s_setprio(1); _Pragma("unroll") for (int m = 0; m < 4; ++m) _Pragma("unroll") for (int n = 0; n < 2; ++n) _Pragma("unroll") for (int k = 0; k < 2; ++k) \
;         acc[ai][bj][m][n] = __builtin_amdgcn_mfma_f32_16x16x32_bf16(Bt[n][k], At[m][k], acc[ai][bj][m][n], 0, 0, 0); __builtin_amdgcn_s_setprio(0); } while (0)
; #define PG8_WAIT_V(n) asm volatile("s_waitcnt vmcnt(" #n ")" ::: "memory")
; #define PG8_WAIT_L(n) asm volatile("s_waitcnt lgkmcnt(" #n ")" ::: "memory")
; #define PG8_BAR __builtin_amdgcn_s_barrier()
; #define PG8_SCHED __builtin_amdgcn_sched_barrier(0)
; template <class Epi, class Sched, bool ALIGN_EPI = true>
; __device__ __forceinline__ void gemm_phase(PG8_LAS unsigned char* lds, const Gemm g, const Sched& S, const Epi& E, const int tid) {
;     ...
;             PG8_LDA(At, 1, 1); PG8_STAGE(PG8_SB(1, 0), b3, voffB); PG8_STAGE(PG8_SB(1, 1), b3 + hstepB, voffB); PG8_STAGE(PG8_SA(1, 0), a3, voffA);
;             PG8_WAIT_V(8); PG8_WAIT_L(0); PG8_BAR; PG8_MMA(1, 0, At, B0); PG8_MMA(1, 1, At, B1); PG8_BAR; PG8_SCHED;
;         }
;         if constexpr (ALIGN_EPI) { if (wr == 0) PG8_BAR; }
	s_add_i32 s15, s15, s60
	v_lshl_add_u64 v[196:197], v[200:201], 0, s[36:37]
	s_mov_b32 m0, s15
	ds_read_b128 v[140:143], v252 offset:49152
	ds_read_b128 v[152:155], v252 offset:50176
	ds_read_b128 v[156:159], v252 offset:51200
	ds_read_b128 v[160:163], v252 offset:52224
	ds_read_b128 v[172:175], v252 offset:53248
	ds_read_b128 v[184:187], v252 offset:54272
	ds_read_b128 v[188:191], v252 offset:55296
	ds_read_b128 v[192:195], v252 offset:56320
	global_load_lds_dwordx4 v[196:197], off
	s_add_i32 m0, s15, 0x2000
	s_add_u32 s22, s22, 0x80080
	v_lshl_add_u64 v[196:197], v[202:203], 0, s[36:37]
	s_addc_u32 s23, s23, 0
	s_add_i32 s15, s16, s60
	global_load_lds_dwordx4 v[196:197], off
	v_lshl_add_u64 v[196:197], s[22:23], 0, v[2:3]
	s_mov_b32 m0, s15
	s_nop 0
	global_load_lds_dwordx4 v[196:197], off
	v_lshl_add_u64 v[196:197], s[22:23], 0, v[214:215]
	s_add_i32 m0, s15, 0x2000
	s_nop 0
	global_load_lds_dwordx4 v[196:197], off
	v_lshl_add_u64 v[196:197], v[204:205], 0, s[36:37]
	s_mov_b32 m0, s68
	s_nop 0
	global_load_lds_dwordx4 v[196:197], off
	v_lshl_add_u64 v[196:197], v[206:207], 0, s[36:37]
	s_mov_b32 m0, s69
	s_nop 0
	global_load_lds_dwordx4 v[196:197], off
	s_waitcnt vmcnt(8)
	s_waitcnt lgkmcnt(0)
	s_barrier
	s_waitcnt lgkmcnt(0)
	v_mfma_f32_16x16x32_bf16 v[80:83], v[60:63], v[140:143], v[80:83]
	v_mfma_f32_16x16x32_bf16 v[80:83], v[64:67], v[152:155], v[80:83]
	v_mfma_f32_16x16x32_bf16 v[76:79], v[68:71], v[140:143], v[76:79]
	v_mfma_f32_16x16x32_bf16 v[76:79], v[72:75], v[152:155], v[76:79]
	v_mfma_f32_16x16x32_bf16 v[48:51], v[60:63], v[156:159], v[48:51]
	v_mfma_f32_16x16x32_bf16 v[48:51], v[64:67], v[160:163], v[48:51]
	v_mfma_f32_16x16x32_bf16 v[44:47], v[68:71], v[156:159], v[44:47]
	v_mfma_f32_16x16x32_bf16 v[44:47], v[72:75], v[160:163], v[44:47]
	v_mfma_f32_16x16x32_bf16 v[32:35], v[60:63], v[172:175], v[32:35]
	v_mfma_f32_16x16x32_bf16 v[32:35], v[64:67], v[184:187], v[32:35]
	v_mfma_f32_16x16x32_bf16 v[28:31], v[68:71], v[172:175], v[28:31]
	v_mfma_f32_16x16x32_bf16 v[28:31], v[72:75], v[184:187], v[28:31]
	v_mfma_f32_16x16x32_bf16 v[16:19], v[60:63], v[188:191], v[16:19]
	v_mfma_f32_16x16x32_bf16 v[16:19], v[64:67], v[192:195], v[16:19]
	v_mfma_f32_16x16x32_bf16 v[12:15], v[68:71], v[188:191], v[12:15]
	v_mfma_f32_16x16x32_bf16 v[12:15], v[72:75], v[192:195], v[12:15]
	v_mfma_f32_16x16x32_bf16 v[56:59], v[92:95], v[140:143], v[56:59]
	v_mfma_f32_16x16x32_bf16 v[60:63], v[104:107], v[152:155], v[56:59]
	v_mfma_f32_16x16x32_bf16 v[52:55], v[116:119], v[140:143], v[52:55]
	v_mfma_f32_16x16x32_bf16 v[52:55], v[128:131], v[152:155], v[52:55]
	v_mfma_f32_16x16x32_bf16 v[40:43], v[92:95], v[156:159], v[40:43]
	v_mfma_f32_16x16x32_bf16 v[40:43], v[104:107], v[160:163], v[40:43]
	v_mfma_f32_16x16x32_bf16 v[36:39], v[116:119], v[156:159], v[36:39]
	v_mfma_f32_16x16x32_bf16 v[36:39], v[128:131], v[160:163], v[36:39]
	v_mfma_f32_16x16x32_bf16 v[24:27], v[92:95], v[172:175], v[24:27]
	v_mfma_f32_16x16x32_bf16 v[24:27], v[104:107], v[184:187], v[24:27]
	v_mfma_f32_16x16x32_bf16 v[20:23], v[116:119], v[172:175], v[20:23]
	v_mfma_f32_16x16x32_bf16 v[20:23], v[128:131], v[184:187], v[20:23]
	v_mfma_f32_16x16x32_bf16 v[8:11], v[92:95], v[188:191], v[8:11]
	v_mfma_f32_16x16x32_bf16 v[8:11], v[104:107], v[192:195], v[8:11]
	v_mfma_f32_16x16x32_bf16 v[4:7], v[116:119], v[188:191], v[4:7]
	v_mfma_f32_16x16x32_bf16 v[4:7], v[128:131], v[192:195], v[4:7]
	s_barrier
	s_add_u32 s12, s12, 0x100
	s_addc_u32 s13, s13, 0
	s_add_u32 s20, s20, 0x100
	s_addc_u32 s21, s21, 0
	s_cmp_ge_i32 s45, s9
	s_mov_b32 s22, s45
	s_cbranch_scc0 .LBB0_1087
	s_and_b64 vcc, exec, s[42:43]
	s_cbranch_vccz .LBB0_1090
	s_barrier

; #define PG8_STAGE(bufoff, gbase, voff) do { _Pragma("unroll") for (int _i = 0; _i < 2; ++_i) \
;         __builtin_amdgcn_global_load_lds((const unsigned*)((const char*)(gbase) + (voff)[_i]), (PG8_LAS unsigned*)(lds + (bufoff) + ldsw + _i * 8192), 16, 0, 0); } while (0)
; #define PG8_LDA(dst, b, h) do { _Pragma("unroll") for (int m = 0; m < 4; ++m) _Pragma("unroll") for (int k = 0; k < 2; ++k) dst[m][k] = *(const PG8_LAS bf16x8*)(lds + PG8_SA(b, h) + aoff + m * 2048 + k * 1024); } while (0)
; #define PG8_LDB(dst, b, h) do { _Pragma("unroll") for (int n = 0; n < 2; ++n) _Pragma("unroll") for (int k = 0; k < 2; ++k) dst[n][k] = *(const PG8_LAS bf16x8*)(lds + PG8_SB(b, h) + boff + n * 2048 + k * 1024); } while (0)
; #define PG8_MMA(ai, bj, At, Bt) do { __builtin_amdgcn_s_setprio(1); _Pragma("unroll") for (int m = 0; m < 4; ++m) _Pragma("unroll") for (int n = 0; n < 2; ++n) _Pragma("unroll") for (int k = 0; k < 2; ++k) \
;         acc[ai][bj][m][n] = __builtin_amdgcn_mfma_f32_16x16x32_bf16(Bt[n][k], At[m][k], acc[ai][bj][m][n], 0, 0, 0); __builtin_amdgcn_s_setprio(0); } while (0)
; #define PG8_WAIT_V(n) asm volatile("s_waitcnt vmcnt(" #n ")" ::: "memory")
; #define PG8_WAIT_L(n) asm volatile("s_waitcnt lgkmcnt(" #n ")" ::: "memory")
; template <class Epi, class Sched, bool ALIGN_EPI = true>
; __device__ __forceinline__ void gemm_phase(PG8_LAS unsigned char* lds, const Gemm g, const Sched& S, const Epi& E, const int tid) {
;     ...
;         for (int t = 0; t < nt; t += 2) {
;             const bool last = (t == nt - 2);
;             const char* a1 = cA + (size_t)(t + 1) * kstep;
;             const char* a2 = last ? nA : cA + (size_t)(t + 2) * kstep; const char* b2 = last ? nB : cB + (size_t)(t + 2) * kstep;
;             const char* a3 = a2 + kstep; const char* b3 = b2 + kstep;
;             if (last && has_next) S.a_ready(nxt);
;             PG8_LDB(B0, 0, 0); PG8_LDB(B1, 0, 1); PG8_SCHED; PG8_LDA(At, 0, 0); PG8_STAGE(PG8_SA(1, 1), a1 + hstepA, voffA);
;             PG8_WAIT_V(8); PG8_WAIT_L(0); PG8_BAR; PG8_MMA(0, 0, At, B0); PG8_MMA(0, 1, At, B1); PG8_BAR; PG8_SCHED;
;             PG8_LDA(At, 0, 1); PG8_STAGE(PG8_SB(0, 0), b2, voffB); PG8_STAGE(PG8_SB(0, 1), b2 + hstepB, voffB); PG8_STAGE(PG8_SA(0, 0), a2, voffA);
;             PG8_WAIT_V(8); PG8_WAIT_L(0); PG8_BAR; PG8_MMA(1, 0, At, B0); PG8_MMA(1, 1, At, B1); PG8_BAR; PG8_SCHED;
.LBB0_1414:
	s_add_i32 s70, s12, 2
	s_add_u32 s10, s0, 0x100
	s_addc_u32 s11, s1, 0
	s_add_i32 s15, 0, 0x10000
	s_cmp_eq_u32 s45, s12
	s_cselect_b32 s23, s47, s11
	s_cselect_b32 s22, s46, s10
	s_cselect_b32 s13, s49, s69
	s_cselect_b32 s12, s48, s68
	s_add_i32 s16, 0, 0x14000
	v_add_u32_e32 v72, s15, v251
	v_add_u32_e32 v128, s16, v251
	ds_read_b128 v[56:59], v72
	ds_read_b128 v[60:63], v72 offset:1024
	ds_read_b128 v[68:71], v72 offset:2048
	ds_read_b128 v[72:75], v72 offset:3072
	ds_read_b128 v[92:95], v128
	ds_read_b128 v[104:107], v128 offset:1024
	ds_read_b128 v[116:119], v128 offset:2048
	ds_read_b128 v[128:131], v128 offset:3072
	v_lshl_add_u64 v[196:197], s[0:1], 0, v[216:217]
	s_add_i32 m0, s52, 0xc000
	ds_read_b128 v[140:143], v252
	ds_read_b128 v[152:155], v252 offset:1024
	ds_read_b128 v[156:159], v252 offset:2048
	ds_read_b128 v[160:163], v252 offset:3072
	ds_read_b128 v[172:175], v252 offset:4096
	ds_read_b128 v[184:187], v252 offset:5120
	ds_read_b128 v[188:191], v252 offset:6144
	ds_read_b128 v[192:195], v252 offset:7168
	global_load_lds_dwordx4 v[196:197], off
	v_lshl_add_u64 v[196:197], s[0:1], 0, v[218:219]
	s_add_i32 m0, s52, 0xe000
	s_nop 0
	global_load_lds_dwordx4 v[196:197], off
	s_waitcnt vmcnt(8)
	s_waitcnt lgkmcnt(0)
	s_barrier
	s_waitcnt lgkmcnt(0)
	v_mfma_f32_16x16x32_bf16 v[180:183], v[56:59], v[140:143], v[180:183]
	v_mfma_f32_16x16x32_bf16 v[180:183], v[60:63], v[152:155], v[180:183]
	v_mfma_f32_16x16x32_bf16 v[176:179], v[68:71], v[140:143], v[176:179]
	v_mfma_f32_16x16x32_bf16 v[176:179], v[72:75], v[152:155], v[176:179]
	v_mfma_f32_16x16x32_bf16 v[148:151], v[56:59], v[156:159], v[148:151]
	v_mfma_f32_16x16x32_bf16 v[148:151], v[60:63], v[160:163], v[148:151]
	v_mfma_f32_16x16x32_bf16 v[144:147], v[68:71], v[156:159], v[144:147]
	v_mfma_f32_16x16x32_bf16 v[144:147], v[72:75], v[160:163], v[144:147]
	v_mfma_f32_16x16x32_bf16 v[124:127], v[56:59], v[172:175], v[124:127]
	v_mfma_f32_16x16x32_bf16 v[124:127], v[60:63], v[184:187], v[124:127]
	v_mfma_f32_16x16x32_bf16 v[120:123], v[68:71], v[172:175], v[120:123]
	v_mfma_f32_16x16x32_bf16 v[120:123], v[72:75], v[184:187], v[120:123]
	v_mfma_f32_16x16x32_bf16 v[100:103], v[56:59], v[188:191], v[100:103]
	v_mfma_f32_16x16x32_bf16 v[100:103], v[60:63], v[192:195], v[100:103]
	v_mfma_f32_16x16x32_bf16 v[96:99], v[68:71], v[188:191], v[96:99]
	v_mfma_f32_16x16x32_bf16 v[96:99], v[72:75], v[192:195], v[96:99]
	v_mfma_f32_16x16x32_bf16 v[168:171], v[92:95], v[140:143], v[168:171]
	v_mfma_f32_16x16x32_bf16 v[168:171], v[104:107], v[152:155], v[168:171]
	v_mfma_f32_16x16x32_bf16 v[136:139], v[92:95], v[156:159], v[136:139]
	v_mfma_f32_16x16x32_bf16 v[136:139], v[104:107], v[160:163], v[136:139]
	v_mfma_f32_16x16x32_bf16 v[132:135], v[116:119], v[156:159], v[132:135]
	v_mfma_f32_16x16x32_bf16 v[132:135], v[128:131], v[160:163], v[132:135]
	v_mfma_f32_16x16x32_bf16 v[112:115], v[92:95], v[172:175], v[112:115]
	v_mfma_f32_16x16x32_bf16 v[112:115], v[104:107], v[184:187], v[112:115]
	v_mfma_f32_16x16x32_bf16 v[108:111], v[116:119], v[172:175], v[108:111]
	v_mfma_f32_16x16x32_bf16 v[108:111], v[128:131], v[184:187], v[108:111]
	v_mfma_f32_16x16x32_bf16 v[88:91], v[92:95], v[188:191], v[88:91]
	v_mfma_f32_16x16x32_bf16 v[88:91], v[104:107], v[192:195], v[88:91]
	v_mfma_f32_16x16x32_bf16 v[84:87], v[116:119], v[188:191], v[84:87]
	v_mfma_f32_16x16x32_bf16 v[84:87], v[128:131], v[192:195], v[84:87]
	v_mfma_f32_16x16x32_bf16 v[140:143], v[116:119], v[140:143], v[164:167]
	v_mfma_f32_16x16x32_bf16 v[140:143], v[128:131], v[152:155], v[140:143]
	s_barrier
	s_add_i32 s0, s15, s51
	v_lshl_add_u64 v[200:201], s[12:13], 0, v[2:3]
	s_mov_b32 m0, s0
	ds_read_b128 v[152:155], v252 offset:16384
	ds_read_b128 v[156:159], v252 offset:17408
	ds_read_b128 v[160:163], v252 offset:18432
	ds_read_b128 v[164:167], v252 offset:19456
	ds_read_b128 v[172:175], v252 offset:20480
	ds_read_b128 v[184:187], v252 offset:21504
	ds_read_b128 v[188:191], v252 offset:22528
	ds_read_b128 v[192:195], v252 offset:23552
	global_load_lds_dwordx4 v[200:201], off
	s_add_i32 m0, s0, 0x2000
	s_add_u32 s0, s12, 0x168000
	v_lshl_add_u64 v[202:203], s[12:13], 0, v[214:215]
	s_addc_u32 s1, s13, 0
	s_add_i32 s15, s16, s51
	global_load_lds_dwordx4 v[202:203], off
	v_lshl_add_u64 v[196:197], s[0:1], 0, v[2:3]
	s_mov_b32 m0, s15
	v_lshl_add_u64 v[204:205], s[22:23], 0, v[210:211]
	global_load_lds_dwordx4 v[196:197], off
	v_lshl_add_u64 v[196:197], s[0:1], 0, v[214:215]
	s_add_i32 m0, s15, 0x2000
	v_lshl_add_u64 v[206:207], s[22:23], 0, v[212:213]
	global_load_lds_dwordx4 v[196:197], off
	s_mov_b32 m0, s52
	s_nop 0
	global_load_lds_dwordx4 v[204:205], off
	s_mov_b32 m0, s53
	s_nop 0
	global_load_lds_dwordx4 v[206:207], off
	s_waitcnt vmcnt(8)
	s_waitcnt lgkmcnt(0)
	s_barrier
; #define PG8_STAGE(bufoff, gbase, voff) do { _Pragma("unroll") for (int _i = 0; _i < 2; ++_i) \
;         __builtin_amdgcn_global_load_lds((const unsigned*)((const char*)(gbase) + (voff)[_i]), (PG8_LAS unsigned*)(lds + (bufoff) + ldsw + _i * 8192), 16, 0, 0); } while (0)
; #define PG8_LDA(dst, b, h) do { _Pragma("unroll") for (int m = 0; m < 4; ++m) _Pragma("unroll") for (int k = 0; k < 2; ++k) dst[m][k] = *(const PG8_LAS bf16x8*)(lds + PG8_SA(b, h) + aoff + m * 2048 + k * 1024); } while (0)
; #define PG8_LDB(dst, b, h) do { _Pragma("unroll") for (int n = 0; n < 2; ++n) _Pragma("unroll") for (int k = 0; k < 2; ++k) dst[n][k] = *(const PG8_LAS bf16x8*)(lds + PG8_SB(b, h) + boff + n * 2048 + k * 1024); } while (0)
; #define PG8_MMA(ai, bj, At, Bt) do { __builtin_amdgcn_s_setprio(1); _Pragma("unroll") for (int m = 0; m < 4; ++m) _Pragma("unroll") for (int n = 0; n < 2; ++n) _Pragma("unroll") for (int k = 0; k < 2; ++k) \
;         acc[ai][bj][m][n] = __builtin_amdgcn_mfma_f32_16x16x32_bf16(Bt[n][k], At[m][k], acc[ai][bj][m][n], 0, 0, 0); __builtin_amdgcn_s_setprio(0); } while (0)
; #define PG8_WAIT_V(n) asm volatile("s_waitcnt vmcnt(" #n ")" ::: "memory")
; #define PG8_WAIT_L(n) asm volatile("s_waitcnt lgkmcnt(" #n ")" ::: "memory")
; #define PG8_BAR __builtin_amdgcn_s_barrier()
; #define PG8_SCHED __builtin_amdgcn_sched_barrier(0)
; template <class Epi, class Sched, bool ALIGN_EPI = true>
; __device__ __forceinline__ void gemm_phase(PG8_LAS unsigned char* lds, const Gemm g, const Sched& S, const Epi& E, const int tid) {
;     ...
;             PG8_WAIT_V(8); PG8_WAIT_L(0); PG8_BAR; PG8_MMA(1, 0, At, B0); PG8_MMA(1, 1, At, B1); PG8_BAR; PG8_SCHED;
;             PG8_LDB(B0, 1, 0); PG8_LDB(B1, 1, 1); PG8_SCHED; PG8_LDA(At, 1, 0); PG8_STAGE(PG8_SA(0, 1), a2 + hstepA, voffA);
;             PG8_WAIT_V(8); PG8_WAIT_L(0); PG8_BAR; PG8_MMA(0, 0, At, B0); PG8_MMA(0, 1, At, B1); PG8_BAR; PG8_SCHED;
	s_waitcnt lgkmcnt(0)
	v_mfma_f32_16x16x32_bf16 v[80:83], v[56:59], v[152:155], v[80:83]
	v_mfma_f32_16x16x32_bf16 v[80:83], v[60:63], v[156:159], v[80:83]
	v_mfma_f32_16x16x32_bf16 v[76:79], v[68:71], v[152:155], v[76:79]
	v_mfma_f32_16x16x32_bf16 v[76:79], v[72:75], v[156:159], v[76:79]
	v_mfma_f32_16x16x32_bf16 v[48:51], v[56:59], v[160:163], v[48:51]
	v_mfma_f32_16x16x32_bf16 v[48:51], v[60:63], v[164:167], v[48:51]
	v_mfma_f32_16x16x32_bf16 v[44:47], v[68:71], v[160:163], v[44:47]
	v_mfma_f32_16x16x32_bf16 v[44:47], v[72:75], v[164:167], v[44:47]
	v_mfma_f32_16x16x32_bf16 v[32:35], v[56:59], v[172:175], v[32:35]
	v_mfma_f32_16x16x32_bf16 v[32:35], v[60:63], v[184:187], v[32:35]
	v_mfma_f32_16x16x32_bf16 v[28:31], v[68:71], v[172:175], v[28:31]
	v_mfma_f32_16x16x32_bf16 v[28:31], v[72:75], v[184:187], v[28:31]
	v_mfma_f32_16x16x32_bf16 v[16:19], v[56:59], v[188:191], v[16:19]
	v_mfma_f32_16x16x32_bf16 v[16:19], v[60:63], v[192:195], v[16:19]
	v_mfma_f32_16x16x32_bf16 v[12:15], v[68:71], v[188:191], v[12:15]
	v_mfma_f32_16x16x32_bf16 v[12:15], v[72:75], v[192:195], v[12:15]
	v_mfma_f32_16x16x32_bf16 v[52:55], v[116:119], v[152:155], v[52:55]
	v_mfma_f32_16x16x32_bf16 v[52:55], v[128:131], v[156:159], v[52:55]
	v_mfma_f32_16x16x32_bf16 v[40:43], v[92:95], v[160:163], v[40:43]
	v_mfma_f32_16x16x32_bf16 v[40:43], v[104:107], v[164:167], v[40:43]
	v_mfma_f32_16x16x32_bf16 v[36:39], v[116:119], v[160:163], v[36:39]
	v_mfma_f32_16x16x32_bf16 v[36:39], v[128:131], v[164:167], v[36:39]
	v_mfma_f32_16x16x32_bf16 v[24:27], v[92:95], v[172:175], v[24:27]
	v_mfma_f32_16x16x32_bf16 v[24:27], v[104:107], v[184:187], v[24:27]
	v_mfma_f32_16x16x32_bf16 v[20:23], v[116:119], v[172:175], v[20:23]
	v_mfma_f32_16x16x32_bf16 v[20:23], v[128:131], v[184:187], v[20:23]
	v_mfma_f32_16x16x32_bf16 v[8:11], v[92:95], v[188:191], v[8:11]
	v_mfma_f32_16x16x32_bf16 v[8:11], v[104:107], v[192:195], v[8:11]
	v_mfma_f32_16x16x32_bf16 v[4:7], v[116:119], v[188:191], v[4:7]
	v_mfma_f32_16x16x32_bf16 v[4:7], v[128:131], v[192:195], v[4:7]
	v_mfma_f32_16x16x32_bf16 v[56:59], v[92:95], v[152:155], v[64:67]
	v_mfma_f32_16x16x32_bf16 v[56:59], v[104:107], v[156:159], v[56:59]
	s_barrier
	s_add_i32 s15, 0, 0x18000
	s_add_i32 s16, 0, 0x1c000
	v_add_u32_e32 v72, s15, v251
	v_add_u32_e32 v128, s16, v251
	ds_read_b128 v[60:63], v72
	ds_read_b128 v[64:67], v72 offset:1024
	ds_read_b128 v[68:71], v72 offset:2048
	ds_read_b128 v[72:75], v72 offset:3072
	ds_read_b128 v[92:95], v128
	ds_read_b128 v[104:107], v128 offset:1024
	ds_read_b128 v[116:119], v128 offset:2048
	ds_read_b128 v[128:131], v128 offset:3072
	s_add_u32 s0, s22, 0x168000
	s_addc_u32 s1, s23, 0
	s_mov_b32 m0, s54
	v_lshl_add_u64 v[164:165], s[0:1], 0, v[210:211]
	ds_read_b128 v[152:155], v252 offset:32768
	ds_read_b128 v[156:159], v252 offset:33792
	ds_read_b128 v[160:163], v252 offset:34816
	ds_read_b128 v[172:175], v252 offset:35840
	ds_read_b128 v[184:187], v252 offset:36864
	ds_read_b128 v[188:191], v252 offset:37888
	ds_read_b128 v[192:195], v252 offset:38912
	ds_read_b128 v[196:199], v252 offset:39936
	global_load_lds_dwordx4 v[164:165], off
	v_lshl_add_u64 v[164:165], s[0:1], 0, v[212:213]
	s_mov_b32 m0, s55
	s_nop 0
	global_load_lds_dwordx4 v[164:165], off
	s_waitcnt vmcnt(8)
	s_waitcnt lgkmcnt(0)
	s_barrier
	s_waitcnt lgkmcnt(0)
	v_mfma_f32_16x16x32_bf16 v[164:167], v[60:63], v[152:155], v[180:183]
	v_mfma_f32_16x16x32_bf16 v[180:183], v[64:67], v[156:159], v[164:167]
	v_mfma_f32_16x16x32_bf16 v[164:167], v[68:71], v[152:155], v[176:179]
	v_mfma_f32_16x16x32_bf16 v[176:179], v[72:75], v[156:159], v[164:167]
	v_mfma_f32_16x16x32_bf16 v[148:151], v[60:63], v[160:163], v[148:151]
	v_mfma_f32_16x16x32_bf16 v[148:151], v[64:67], v[172:175], v[148:151]
	v_mfma_f32_16x16x32_bf16 v[144:147], v[68:71], v[160:163], v[144:147]
	v_mfma_f32_16x16x32_bf16 v[144:147], v[72:75], v[172:175], v[144:147]
	v_mfma_f32_16x16x32_bf16 v[124:127], v[60:63], v[184:187], v[124:127]
	v_mfma_f32_16x16x32_bf16 v[124:127], v[64:67], v[188:191], v[124:127]
	v_mfma_f32_16x16x32_bf16 v[120:123], v[68:71], v[184:187], v[120:123]
	v_mfma_f32_16x16x32_bf16 v[120:123], v[72:75], v[188:191], v[120:123]
	v_mfma_f32_16x16x32_bf16 v[100:103], v[60:63], v[192:195], v[100:103]
	v_mfma_f32_16x16x32_bf16 v[100:103], v[64:67], v[196:199], v[100:103]
	v_mfma_f32_16x16x32_bf16 v[96:99], v[68:71], v[192:195], v[96:99]
	v_mfma_f32_16x16x32_bf16 v[96:99], v[72:75], v[196:199], v[96:99]
	v_mfma_f32_16x16x32_bf16 v[164:167], v[92:95], v[152:155], v[168:171]
	v_mfma_f32_16x16x32_bf16 v[168:171], v[104:107], v[156:159], v[164:167]
	v_mfma_f32_16x16x32_bf16 v[140:143], v[116:119], v[152:155], v[140:143]
	v_mfma_f32_16x16x32_bf16 v[164:167], v[128:131], v[156:159], v[140:143]
	v_mfma_f32_16x16x32_bf16 v[136:139], v[92:95], v[160:163], v[136:139]
	v_mfma_f32_16x16x32_bf16 v[136:139], v[104:107], v[172:175], v[136:139]
	v_mfma_f32_16x16x32_bf16 v[132:135], v[116:119], v[160:163], v[132:135]
	v_mfma_f32_16x16x32_bf16 v[132:135], v[128:131], v[172:175], v[132:135]
	v_mfma_f32_16x16x32_bf16 v[112:115], v[92:95], v[184:187], v[112:115]
	v_mfma_f32_16x16x32_bf16 v[112:115], v[104:107], v[188:191], v[112:115]
	v_mfma_f32_16x16x32_bf16 v[108:111], v[116:119], v[184:187], v[108:111]
	v_mfma_f32_16x16x32_bf16 v[108:111], v[128:131], v[188:191], v[108:111]
	v_mfma_f32_16x16x32_bf16 v[88:91], v[92:95], v[192:195], v[88:91]
	v_mfma_f32_16x16x32_bf16 v[88:91], v[104:107], v[196:199], v[88:91]
	v_mfma_f32_16x16x32_bf16 v[84:87], v[116:119], v[192:195], v[84:87]
	v_mfma_f32_16x16x32_bf16 v[84:87], v[128:131], v[196:199], v[84:87]
	s_barrier
; #define PG8_STAGE(bufoff, gbase, voff) do { _Pragma("unroll") for (int _i = 0; _i < 2; ++_i) \
;         __builtin_amdgcn_global_load_lds((const unsigned*)((const char*)(gbase) + (voff)[_i]), (PG8_LAS unsigned*)(lds + (bufoff) + ldsw + _i * 8192), 16, 0, 0); } while (0)
; #define PG8_LDA(dst, b, h) do { _Pragma("unroll") for (int m = 0; m < 4; ++m) _Pragma("unroll") for (int k = 0; k < 2; ++k) dst[m][k] = *(const PG8_LAS bf16x8*)(lds + PG8_SA(b, h) + aoff + m * 2048 + k * 1024); } while (0)
; #define PG8_MMA(ai, bj, At, Bt) do { __builtin_amdgcn_s_setprio(1); _Pragma("unroll") for (int m = 0; m < 4; ++m) _Pragma("unroll") for (int n = 0; n < 2; ++n) _Pragma("unroll") for (int k = 0; k < 2; ++k) \
;         acc[ai][bj][m][n] = __builtin_amdgcn_mfma_f32_16x16x32_bf16(Bt[n][k], At[m][k], acc[ai][bj][m][n], 0, 0, 0); __builtin_amdgcn_s_setprio(0); } while (0)
; #define PG8_WAIT_V(n) asm volatile("s_waitcnt vmcnt(" #n ")" ::: "memory")
; #define PG8_WAIT_L(n) asm volatile("s_waitcnt lgkmcnt(" #n ")" ::: "memory")
; #define PG8_BAR __builtin_amdgcn_s_barrier()
; #define PG8_SCHED __builtin_amdgcn_sched_barrier(0)
; template <class Epi, class Sched, bool ALIGN_EPI = true>
; __device__ __forceinline__ void gemm_phase(PG8_LAS unsigned char* lds, const Gemm g, const Sched& S, const Epi& E, const int tid) {
;     ...
;             PG8_LDA(At, 1, 1); PG8_STAGE(PG8_SB(1, 0), b3, voffB); PG8_STAGE(PG8_SB(1, 1), b3 + hstepB, voffB); PG8_STAGE(PG8_SA(1, 0), a3, voffA);
;             PG8_WAIT_V(8); PG8_WAIT_L(0); PG8_BAR; PG8_MMA(1, 0, At, B0); PG8_MMA(1, 1, At, B1); PG8_BAR; PG8_SCHED;
;         }
;         if constexpr (ALIGN_EPI) { if (wr == 0) PG8_BAR; }
	s_add_i32 s0, s15, s51
	v_lshl_add_u64 v[196:197], v[200:201], 0, s[36:37]
	s_mov_b32 m0, s0
	ds_read_b128 v[140:143], v252 offset:49152
	ds_read_b128 v[152:155], v252 offset:50176
	ds_read_b128 v[156:159], v252 offset:51200
	ds_read_b128 v[160:163], v252 offset:52224
	ds_read_b128 v[172:175], v252 offset:53248
	ds_read_b128 v[184:187], v252 offset:54272
	ds_read_b128 v[188:191], v252 offset:55296
	ds_read_b128 v[192:195], v252 offset:56320
	global_load_lds_dwordx4 v[196:197], off
	s_add_i32 m0, s0, 0x2000
	s_add_u32 s0, s12, 0x168080
	v_lshl_add_u64 v[196:197], v[202:203], 0, s[36:37]
	s_addc_u32 s1, s13, 0
	s_add_i32 s12, s16, s51
	global_load_lds_dwordx4 v[196:197], off
	v_lshl_add_u64 v[196:197], s[0:1], 0, v[2:3]
	s_mov_b32 m0, s12
	s_nop 0
	global_load_lds_dwordx4 v[196:197], off
	v_lshl_add_u64 v[196:197], s[0:1], 0, v[214:215]
	s_add_i32 m0, s12, 0x2000
	s_nop 0
	global_load_lds_dwordx4 v[196:197], off
	v_lshl_add_u64 v[196:197], v[204:205], 0, s[36:37]
	s_mov_b32 m0, s58
	s_nop 0
	global_load_lds_dwordx4 v[196:197], off
	v_lshl_add_u64 v[196:197], v[206:207], 0, s[36:37]
	s_mov_b32 m0, s59
	s_nop 0
	global_load_lds_dwordx4 v[196:197], off
	s_waitcnt vmcnt(8)
	s_waitcnt lgkmcnt(0)
	s_barrier
	s_waitcnt lgkmcnt(0)
	v_mfma_f32_16x16x32_bf16 v[80:83], v[60:63], v[140:143], v[80:83]
	v_mfma_f32_16x16x32_bf16 v[80:83], v[64:67], v[152:155], v[80:83]
	v_mfma_f32_16x16x32_bf16 v[76:79], v[68:71], v[140:143], v[76:79]
	v_mfma_f32_16x16x32_bf16 v[76:79], v[72:75], v[152:155], v[76:79]
	v_mfma_f32_16x16x32_bf16 v[48:51], v[60:63], v[156:159], v[48:51]
	v_mfma_f32_16x16x32_bf16 v[48:51], v[64:67], v[160:163], v[48:51]
	v_mfma_f32_16x16x32_bf16 v[44:47], v[68:71], v[156:159], v[44:47]
	v_mfma_f32_16x16x32_bf16 v[44:47], v[72:75], v[160:163], v[44:47]
	v_mfma_f32_16x16x32_bf16 v[32:35], v[60:63], v[172:175], v[32:35]
	v_mfma_f32_16x16x32_bf16 v[32:35], v[64:67], v[184:187], v[32:35]
	v_mfma_f32_16x16x32_bf16 v[28:31], v[68:71], v[172:175], v[28:31]
	v_mfma_f32_16x16x32_bf16 v[28:31], v[72:75], v[184:187], v[28:31]
	v_mfma_f32_16x16x32_bf16 v[16:19], v[60:63], v[188:191], v[16:19]
	v_mfma_f32_16x16x32_bf16 v[16:19], v[64:67], v[192:195], v[16:19]
	v_mfma_f32_16x16x32_bf16 v[12:15], v[68:71], v[188:191], v[12:15]
	v_mfma_f32_16x16x32_bf16 v[12:15], v[72:75], v[192:195], v[12:15]
	v_mfma_f32_16x16x32_bf16 v[56:59], v[92:95], v[140:143], v[56:59]
	v_mfma_f32_16x16x32_bf16 v[64:67], v[104:107], v[152:155], v[56:59]
	v_mfma_f32_16x16x32_bf16 v[52:55], v[116:119], v[140:143], v[52:55]
	v_mfma_f32_16x16x32_bf16 v[52:55], v[128:131], v[152:155], v[52:55]
	v_mfma_f32_16x16x32_bf16 v[40:43], v[92:95], v[156:159], v[40:43]
	v_mfma_f32_16x16x32_bf16 v[40:43], v[104:107], v[160:163], v[40:43]
	v_mfma_f32_16x16x32_bf16 v[36:39], v[116:119], v[156:159], v[36:39]
	v_mfma_f32_16x16x32_bf16 v[36:39], v[128:131], v[160:163], v[36:39]
	v_mfma_f32_16x16x32_bf16 v[24:27], v[92:95], v[172:175], v[24:27]
	v_mfma_f32_16x16x32_bf16 v[24:27], v[104:107], v[184:187], v[24:27]
	v_mfma_f32_16x16x32_bf16 v[20:23], v[116:119], v[172:175], v[20:23]
	v_mfma_f32_16x16x32_bf16 v[20:23], v[128:131], v[184:187], v[20:23]
	v_mfma_f32_16x16x32_bf16 v[8:11], v[92:95], v[188:191], v[8:11]
	v_mfma_f32_16x16x32_bf16 v[8:11], v[104:107], v[192:195], v[8:11]
	v_mfma_f32_16x16x32_bf16 v[4:7], v[116:119], v[188:191], v[4:7]
	v_mfma_f32_16x16x32_bf16 v[4:7], v[128:131], v[192:195], v[4:7]
	s_barrier
	s_add_u32 s68, s68, 0x100
	s_addc_u32 s69, s69, 0
	s_cmp_ge_i32 s70, s67
	s_mov_b64 s[0:1], s[10:11]
	s_mov_b32 s12, s70
	s_cbranch_scc0 .LBB0_1414
	s_nop 0
	s_nop 0
	s_nop 0
	s_nop 0
	s_nop 0
	s_nop 0
	s_nop 0
	s_nop 0
	s_nop 0
	s_nop 0
	s_nop 0
	s_nop 0
	s_and_b64 vcc, exec, s[42:43]
	s_cbranch_vccz .LBB0_1417
	s_barrier
